# v25 + write-through sc1 on every SwiGLU epilogue store (R1 output is never re-read from L2)
# baseline (speedup 1.0000x reference)
; __device__ __forceinline__ unsigned cvt_pk_bf16(float lo, float hi) { unsigned r; asm volatile("v_cvt_pk_bf16_f32 %0, %1, %2" : "=v"(r) : "v"(lo), "v"(hi)); return r; }
; __device__ __forceinline__ void rs_issue(const float* ssq, int rbase, RsLoad& L) {
;     const int lane = threadIdx.x & 63;
;     const f32x4* p0 = (const f32x4*)(ssq + (size_t)(rbase + lane) * 16); const f32x4* p1 = (const f32x4*)(ssq + (size_t)(rbase + 128 + lane) * 16);
;     L.a0 = p0[0]; L.b0 = p0[1]; L.c0 = p0[2]; L.d0 = p0[3]; L.a1 = p1[0]; L.b1 = p1[1]; L.c1 = p1[2]; L.d1 = p1[3];
;     __device__ __forceinline__ void operator()(Acc& acc, const Unit& u, int wr, int wc, int fr, int fq, LAS unsigned char*, const LAS float* rst) const {
;     ...
;             for (int m = 0; m < 4; ++m) {
;                 const int row = row0 + ai * 128 + m * 16; const float rs = rsv[ai][m];
;                 const float cexp = -1.4426950408889634f * rs, rs2 = rs * rs;
;                 unsigned w[4];
; #pragma unroll
;                 for (int n = 0; n < 2; ++n)
; #pragma unroll
;                     for (int p = 0; p < 2; ++p) { const f32x2 g2 = {acc[ai][0][m][n][2 * p], acc[ai][0][m][n][2 * p + 1]}, u2 = {acc[ai][1][m][n][2 * p], acc[ai][1][m][n][2 * p + 1]};
;                         f32x2 e2 = g2 * cexp; e2.x = __builtin_amdgcn_exp2f(e2.x); e2.y = __builtin_amdgcn_exp2f(e2.y);
;                         const f32x2 d2 = e2 + 1.0f; f32x2 r2; r2.x = __builtin_amdgcn_rcpf(d2.x); r2.y = __builtin_amdgcn_rcpf(d2.y);
;                         const f32x2 o2 = ((g2 * u2) * rs2) * r2; w[n * 2 + p] = cvt_pk_bf16(o2.x, o2.y); }
;                 *(u32x4*)(O + (size_t)row * FF + col0) = (u32x4){w[0], w[1], w[2], w[3]};
.LBB0_777:
	v_lshl_add_u32 v130, s93, 8, v192
	v_ashrrev_i32_e32 v131, 31, v130
	v_lshlrev_b64 v[132:133], 6, v[130:131]
	v_add_u32_e32 v130, 0x80, v130
	v_ashrrev_i32_e32 v131, 31, v130
	v_lshlrev_b64 v[130:131], 6, v[130:131]
	v_lshl_add_u64 v[132:133], s[12:13], 0, v[132:133]
	v_lshl_add_u64 v[134:135], s[12:13], 0, v[130:131]
	global_load_dwordx4 v[154:157], v[132:133], off
	global_load_dwordx4 v[158:161], v[132:133], off offset:16
	global_load_dwordx4 v[146:149], v[132:133], off offset:32
	global_load_dwordx4 v[150:153], v[132:133], off offset:48
	global_load_dwordx4 v[138:141], v[134:135], off
	global_load_dwordx4 v[142:145], v[134:135], off offset:16
	s_nop 0
	global_load_dwordx4 v[130:133], v[134:135], off offset:32
	s_nop 0
	global_load_dwordx4 v[134:137], v[134:135], off offset:48
	ds_read2_b32 v[196:197], v191 offset1:16
	ds_read2_b32 v[176:177], v191 offset0:64 offset1:80
	ds_read2_b32 v[178:179], v191 offset0:32 offset1:48
	v_pk_mul_f32 v[124:125], v[128:129], v[124:125]
	v_pk_mul_f32 v[116:117], v[120:121], v[116:117]
	s_waitcnt lgkmcnt(0)
	v_mul_f32_e32 v198, 0xbfb8aa3b, v196
	v_pk_mul_f32 v[126:127], v[126:127], v[198:199] op_sel_hi:[1,0]
	v_pk_mul_f32 v[128:129], v[128:129], v[198:199] op_sel_hi:[1,0]
	v_exp_f32_e32 v200, v126
	v_exp_f32_e32 v201, v127
	v_exp_f32_e32 v128, v128
	v_exp_f32_e32 v129, v129
	v_mul_f32_e32 v196, v196, v196
	v_pk_add_f32 v[200:201], v[200:201], 1.0 op_sel_hi:[1,0]
	v_pk_mul_f32 v[122:123], v[122:123], v[196:197] op_sel_hi:[1,0]
	v_pk_add_f32 v[128:129], v[128:129], 1.0 op_sel_hi:[1,0]
	v_rcp_f32_e32 v200, v200
	v_rcp_f32_e32 v201, v201
	v_rcp_f32_e32 v128, v128
	v_rcp_f32_e32 v129, v129
	v_pk_mul_f32 v[118:119], v[118:119], v[198:199] op_sel_hi:[1,0]
	v_pk_mul_f32 v[124:125], v[124:125], v[196:197] op_sel_hi:[1,0]
	v_pk_mul_f32 v[122:123], v[122:123], v[200:201]
	v_exp_f32_e32 v118, v118
	v_exp_f32_e32 v119, v119
	v_pk_mul_f32 v[124:125], v[124:125], v[128:129]
	ds_read2_b32 v[126:127], v191 offset0:96 offset1:112
	v_cvt_pk_bf16_f32 v122, v122, v123
	v_cvt_pk_bf16_f32 v123, v124, v125
	v_pk_mul_f32 v[124:125], v[120:121], v[198:199] op_sel_hi:[1,0]
	v_pk_add_f32 v[118:119], v[118:119], 1.0 op_sel_hi:[1,0]
	v_exp_f32_e32 v124, v124
	v_exp_f32_e32 v125, v125
	v_rcp_f32_e32 v118, v118
	v_rcp_f32_e32 v119, v119
	v_pk_mul_f32 v[114:115], v[114:115], v[196:197] op_sel_hi:[1,0]
	v_pk_add_f32 v[120:121], v[124:125], 1.0 op_sel_hi:[1,0]
	v_ashrrev_i32_e32 v175, 31, v174
	v_rcp_f32_e32 v120, v120
	v_rcp_f32_e32 v121, v121
	v_pk_mul_f32 v[114:115], v[114:115], v[118:119]
	v_pk_mul_f32 v[108:109], v[112:113], v[108:109]
	v_cvt_pk_bf16_f32 v124, v114, v115
	v_pk_mul_f32 v[114:115], v[116:117], v[196:197] op_sel_hi:[1,0]
	v_lshlrev_b64 v[116:117], 1, v[174:175]
	v_pk_mul_f32 v[114:115], v[114:115], v[120:121]
	v_mul_f32_e32 v120, 0xbfb8aa3b, v197
	v_pk_mul_f32 v[110:111], v[110:111], v[120:121] op_sel_hi:[1,0]
	v_cvt_pk_bf16_f32 v125, v114, v115
	v_mov_b64_e32 v[114:115], s[16:17]
	v_exp_f32_e32 v110, v110
	v_exp_f32_e32 v111, v111
	v_pk_mul_f32 v[112:113], v[112:113], v[120:121] op_sel_hi:[1,0]
	v_mad_i64_i32 v[118:119], s[0:1], v195, s80, v[114:115]
	v_pk_add_f32 v[110:111], v[110:111], 1.0 op_sel_hi:[1,0]
	v_exp_f32_e32 v112, v112
	v_rcp_f32_e32 v110, v110
	v_rcp_f32_e32 v111, v111
	v_exp_f32_e32 v113, v113
	v_lshl_add_u64 v[118:119], v[118:119], 0, v[116:117]
	global_store_dwordx4 v[118:119], v[122:125], off sc1
	v_mul_f32_e32 v118, v197, v197
	v_pk_mul_f32 v[106:107], v[106:107], v[118:119] op_sel_hi:[1,0]
	v_pk_mul_f32 v[102:103], v[102:103], v[120:121] op_sel_hi:[1,0]
	v_pk_mul_f32 v[106:107], v[106:107], v[110:111]
	v_pk_add_f32 v[110:111], v[112:113], 1.0 op_sel_hi:[1,0]
	v_exp_f32_e32 v102, v102
	v_rcp_f32_e32 v110, v110
	v_rcp_f32_e32 v111, v111
	v_exp_f32_e32 v103, v103
	v_pk_mul_f32 v[108:109], v[108:109], v[118:119] op_sel_hi:[1,0]
	v_cvt_pk_bf16_f32 v106, v106, v107
	v_pk_mul_f32 v[98:99], v[98:99], v[118:119] op_sel_hi:[1,0]
	v_pk_mul_f32 v[108:109], v[108:109], v[110:111]
	v_pk_add_f32 v[102:103], v[102:103], 1.0 op_sel_hi:[1,0]
	v_cvt_pk_bf16_f32 v107, v108, v109
	v_pk_mul_f32 v[108:109], v[104:105], v[120:121] op_sel_hi:[1,0]
	v_rcp_f32_e32 v102, v102
	v_rcp_f32_e32 v103, v103
	v_exp_f32_e32 v108, v108
	v_exp_f32_e32 v109, v109
	v_pk_mul_f32 v[100:101], v[104:105], v[100:101]
	v_pk_mul_f32 v[98:99], v[98:99], v[102:103]
	v_pk_mul_f32 v[92:93], v[96:97], v[92:93]
	v_pk_add_f32 v[104:105], v[108:109], 1.0 op_sel_hi:[1,0]
	v_cvt_pk_bf16_f32 v108, v98, v99
	v_pk_mul_f32 v[98:99], v[100:101], v[118:119] op_sel_hi:[1,0]
	v_mul_f32_e32 v100, 0xbfb8aa3b, v178
	v_rcp_f32_e32 v104, v104
	v_rcp_f32_e32 v105, v105
	v_pk_mul_f32 v[94:95], v[94:95], v[100:101] op_sel_hi:[1,0]
	v_pk_mul_f32 v[96:97], v[96:97], v[100:101] op_sel_hi:[1,0]
	v_exp_f32_e32 v94, v94
	v_exp_f32_e32 v95, v95
	v_pk_mul_f32 v[98:99], v[98:99], v[104:105]
	v_exp_f32_e32 v96, v96
	v_cvt_pk_bf16_f32 v109, v98, v99
	v_or_b32_e32 v98, 16, v195
	v_pk_add_f32 v[94:95], v[94:95], 1.0 op_sel_hi:[1,0]
	v_mad_i64_i32 v[98:99], s[0:1], v98, s80, v[114:115]
	v_rcp_f32_e32 v94, v94
	v_rcp_f32_e32 v95, v95
	v_exp_f32_e32 v97, v97
	v_lshl_add_u64 v[98:99], v[98:99], 0, v[116:117]
	global_store_dwordx4 v[98:99], v[106:109], off sc1
	v_mul_f32_e32 v98, v178, v178
	v_pk_mul_f32 v[90:91], v[90:91], v[98:99] op_sel_hi:[1,0]
	v_pk_mul_f32 v[86:87], v[86:87], v[100:101] op_sel_hi:[1,0]
	v_pk_mul_f32 v[90:91], v[90:91], v[94:95]
	v_pk_add_f32 v[94:95], v[96:97], 1.0 op_sel_hi:[1,0]
	v_exp_f32_e32 v86, v86
	v_rcp_f32_e32 v94, v94
	v_rcp_f32_e32 v95, v95
	v_exp_f32_e32 v87, v87
	v_pk_mul_f32 v[92:93], v[92:93], v[98:99] op_sel_hi:[1,0]
; __device__ __forceinline__ unsigned cvt_pk_bf16(float lo, float hi) { unsigned r; asm volatile("v_cvt_pk_bf16_f32 %0, %1, %2" : "=v"(r) : "v"(lo), "v"(hi)); return r; }
;     __device__ __forceinline__ void operator()(Acc& acc, const Unit& u, int wr, int wc, int fr, int fq, LAS unsigned char*, const LAS float* rst) const {
;     ...
;             for (int m = 0; m < 4; ++m) {
;                 const int row = row0 + ai * 128 + m * 16; const float rs = rsv[ai][m];
;                 const float cexp = -1.4426950408889634f * rs, rs2 = rs * rs;
;                 unsigned w[4];
; #pragma unroll
;                 for (int n = 0; n < 2; ++n)
; #pragma unroll
;                     for (int p = 0; p < 2; ++p) { const f32x2 g2 = {acc[ai][0][m][n][2 * p], acc[ai][0][m][n][2 * p + 1]}, u2 = {acc[ai][1][m][n][2 * p], acc[ai][1][m][n][2 * p + 1]};
;                         f32x2 e2 = g2 * cexp; e2.x = __builtin_amdgcn_exp2f(e2.x); e2.y = __builtin_amdgcn_exp2f(e2.y);
;                         const f32x2 d2 = e2 + 1.0f; f32x2 r2; r2.x = __builtin_amdgcn_rcpf(d2.x); r2.y = __builtin_amdgcn_rcpf(d2.y);
;                         const f32x2 o2 = ((g2 * u2) * rs2) * r2; w[n * 2 + p] = cvt_pk_bf16(o2.x, o2.y); }
;                 *(u32x4*)(O + (size_t)row * FF + col0) = (u32x4){w[0], w[1], w[2], w[3]};
	v_cvt_pk_bf16_f32 v90, v90, v91
	v_pk_mul_f32 v[82:83], v[82:83], v[98:99] op_sel_hi:[1,0]
	v_pk_mul_f32 v[92:93], v[92:93], v[94:95]
	v_pk_add_f32 v[86:87], v[86:87], 1.0 op_sel_hi:[1,0]
	v_cvt_pk_bf16_f32 v91, v92, v93
	v_pk_mul_f32 v[92:93], v[88:89], v[100:101] op_sel_hi:[1,0]
	v_rcp_f32_e32 v86, v86
	v_rcp_f32_e32 v87, v87
	v_exp_f32_e32 v92, v92
	v_exp_f32_e32 v93, v93
	v_pk_mul_f32 v[84:85], v[88:89], v[84:85]
	v_pk_mul_f32 v[82:83], v[82:83], v[86:87]
	v_pk_mul_f32 v[76:77], v[80:81], v[76:77]
	v_pk_add_f32 v[88:89], v[92:93], 1.0 op_sel_hi:[1,0]
	v_cvt_pk_bf16_f32 v92, v82, v83
	v_pk_mul_f32 v[82:83], v[84:85], v[98:99] op_sel_hi:[1,0]
	v_mul_f32_e32 v84, 0xbfb8aa3b, v179
	v_rcp_f32_e32 v88, v88
	v_rcp_f32_e32 v89, v89
	v_pk_mul_f32 v[78:79], v[78:79], v[84:85] op_sel_hi:[1,0]
	v_pk_mul_f32 v[80:81], v[80:81], v[84:85] op_sel_hi:[1,0]
	v_exp_f32_e32 v78, v78
	v_exp_f32_e32 v79, v79
	v_pk_mul_f32 v[82:83], v[82:83], v[88:89]
	v_exp_f32_e32 v80, v80
	v_cvt_pk_bf16_f32 v93, v82, v83
	v_or_b32_e32 v82, 32, v195
	v_pk_add_f32 v[78:79], v[78:79], 1.0 op_sel_hi:[1,0]
	v_mad_i64_i32 v[82:83], s[0:1], v82, s80, v[114:115]
	v_rcp_f32_e32 v78, v78
	v_rcp_f32_e32 v79, v79
	v_exp_f32_e32 v81, v81
	v_lshl_add_u64 v[82:83], v[82:83], 0, v[116:117]
	global_store_dwordx4 v[82:83], v[90:93], off sc1
	v_mul_f32_e32 v82, v179, v179
	v_pk_mul_f32 v[74:75], v[74:75], v[82:83] op_sel_hi:[1,0]
	v_pk_mul_f32 v[70:71], v[70:71], v[84:85] op_sel_hi:[1,0]
	v_pk_mul_f32 v[74:75], v[74:75], v[78:79]
	v_pk_add_f32 v[78:79], v[80:81], 1.0 op_sel_hi:[1,0]
	v_exp_f32_e32 v70, v70
	v_rcp_f32_e32 v78, v78
	v_rcp_f32_e32 v79, v79
	v_exp_f32_e32 v71, v71
	v_pk_mul_f32 v[76:77], v[76:77], v[82:83] op_sel_hi:[1,0]
	v_cvt_pk_bf16_f32 v74, v74, v75
	v_pk_mul_f32 v[66:67], v[66:67], v[82:83] op_sel_hi:[1,0]
	v_pk_mul_f32 v[76:77], v[76:77], v[78:79]
	v_pk_add_f32 v[70:71], v[70:71], 1.0 op_sel_hi:[1,0]
	v_cvt_pk_bf16_f32 v75, v76, v77
	v_pk_mul_f32 v[76:77], v[72:73], v[84:85] op_sel_hi:[1,0]
	v_rcp_f32_e32 v70, v70
	v_rcp_f32_e32 v71, v71
	v_exp_f32_e32 v76, v76
	v_exp_f32_e32 v77, v77
	v_pk_mul_f32 v[68:69], v[72:73], v[68:69]
	v_pk_mul_f32 v[66:67], v[66:67], v[70:71]
	v_pk_mul_f32 v[60:61], v[64:65], v[60:61]
	v_pk_add_f32 v[72:73], v[76:77], 1.0 op_sel_hi:[1,0]
	v_cvt_pk_bf16_f32 v76, v66, v67
	v_pk_mul_f32 v[66:67], v[68:69], v[82:83] op_sel_hi:[1,0]
	v_mul_f32_e32 v68, 0xbfb8aa3b, v176
	v_rcp_f32_e32 v72, v72
	v_rcp_f32_e32 v73, v73
	v_pk_mul_f32 v[62:63], v[62:63], v[68:69] op_sel_hi:[1,0]
	v_pk_mul_f32 v[64:65], v[64:65], v[68:69] op_sel_hi:[1,0]
	v_exp_f32_e32 v62, v62
	v_exp_f32_e32 v63, v63
	v_pk_mul_f32 v[66:67], v[66:67], v[72:73]
	v_exp_f32_e32 v64, v64
	v_cvt_pk_bf16_f32 v77, v66, v67
	v_or_b32_e32 v66, 48, v195
	v_pk_add_f32 v[62:63], v[62:63], 1.0 op_sel_hi:[1,0]
	v_mad_i64_i32 v[66:67], s[0:1], v66, s80, v[114:115]
	v_rcp_f32_e32 v62, v62
	v_rcp_f32_e32 v63, v63
	v_exp_f32_e32 v65, v65
	v_lshl_add_u64 v[66:67], v[66:67], 0, v[116:117]
	global_store_dwordx4 v[66:67], v[74:77], off sc1
	v_add_u32_e32 v67, 0x80, v195
	v_mul_f32_e32 v66, v176, v176
	v_pk_mul_f32 v[58:59], v[58:59], v[66:67] op_sel_hi:[1,0]
	v_pk_mul_f32 v[54:55], v[54:55], v[68:69] op_sel_hi:[1,0]
	v_pk_mul_f32 v[58:59], v[58:59], v[62:63]
	v_pk_add_f32 v[62:63], v[64:65], 1.0 op_sel_hi:[1,0]
	v_exp_f32_e32 v54, v54
	v_rcp_f32_e32 v62, v62
	v_rcp_f32_e32 v63, v63
	v_exp_f32_e32 v55, v55
	v_pk_mul_f32 v[60:61], v[60:61], v[66:67] op_sel_hi:[1,0]
	v_cvt_pk_bf16_f32 v58, v58, v59
	v_pk_mul_f32 v[50:51], v[50:51], v[66:67] op_sel_hi:[1,0]
	v_pk_mul_f32 v[60:61], v[60:61], v[62:63]
	v_pk_add_f32 v[54:55], v[54:55], 1.0 op_sel_hi:[1,0]
	v_cvt_pk_bf16_f32 v59, v60, v61
	v_pk_mul_f32 v[60:61], v[56:57], v[68:69] op_sel_hi:[1,0]
	v_rcp_f32_e32 v54, v54
	v_rcp_f32_e32 v55, v55
	v_exp_f32_e32 v60, v60
	v_exp_f32_e32 v61, v61
	v_pk_mul_f32 v[52:53], v[56:57], v[52:53]
	v_pk_mul_f32 v[50:51], v[50:51], v[54:55]
	v_pk_mul_f32 v[44:45], v[48:49], v[44:45]
	v_pk_add_f32 v[56:57], v[60:61], 1.0 op_sel_hi:[1,0]
	v_cvt_pk_bf16_f32 v60, v50, v51
	v_pk_mul_f32 v[50:51], v[52:53], v[66:67] op_sel_hi:[1,0]
	v_mul_f32_e32 v52, 0xbfb8aa3b, v177
	v_pk_mul_f32 v[46:47], v[46:47], v[52:53] op_sel_hi:[1,0]
	v_rcp_f32_e32 v56, v56
	v_rcp_f32_e32 v57, v57
	v_exp_f32_e32 v46, v46
	v_exp_f32_e32 v47, v47
	v_pk_mul_f32 v[48:49], v[48:49], v[52:53] op_sel_hi:[1,0]
	v_pk_mul_f32 v[50:51], v[50:51], v[56:57]
	v_exp_f32_e32 v48, v48
	v_pk_add_f32 v[46:47], v[46:47], 1.0 op_sel_hi:[1,0]
	v_cvt_pk_bf16_f32 v61, v50, v51
	v_mad_i64_i32 v[50:51], s[0:1], v67, s80, v[114:115]
	v_rcp_f32_e32 v46, v46
	v_rcp_f32_e32 v47, v47
	v_exp_f32_e32 v49, v49
	v_lshl_add_u64 v[50:51], v[50:51], 0, v[116:117]
	global_store_dwordx4 v[50:51], v[58:61], off sc1
	v_mul_f32_e32 v50, v177, v177
	v_pk_mul_f32 v[42:43], v[42:43], v[50:51] op_sel_hi:[1,0]
	v_pk_mul_f32 v[38:39], v[38:39], v[52:53] op_sel_hi:[1,0]
	v_pk_mul_f32 v[42:43], v[42:43], v[46:47]
	v_pk_add_f32 v[46:47], v[48:49], 1.0 op_sel_hi:[1,0]
	v_exp_f32_e32 v38, v38
	v_rcp_f32_e32 v46, v46
	v_rcp_f32_e32 v47, v47
	v_exp_f32_e32 v39, v39
	v_pk_mul_f32 v[44:45], v[44:45], v[50:51] op_sel_hi:[1,0]
	v_cvt_pk_bf16_f32 v42, v42, v43
	v_pk_mul_f32 v[34:35], v[34:35], v[50:51] op_sel_hi:[1,0]
	v_pk_mul_f32 v[44:45], v[44:45], v[46:47]
	v_pk_add_f32 v[38:39], v[38:39], 1.0 op_sel_hi:[1,0]
	v_cvt_pk_bf16_f32 v43, v44, v45
	v_pk_mul_f32 v[44:45], v[40:41], v[52:53] op_sel_hi:[1,0]
	v_rcp_f32_e32 v38, v38
	v_rcp_f32_e32 v39, v39
	v_exp_f32_e32 v44, v44
	v_exp_f32_e32 v45, v45
	v_pk_mul_f32 v[36:37], v[40:41], v[36:37]
	v_pk_mul_f32 v[34:35], v[34:35], v[38:39]
	v_pk_mul_f32 v[28:29], v[32:33], v[28:29]
	v_pk_add_f32 v[40:41], v[44:45], 1.0 op_sel_hi:[1,0]
	v_cvt_pk_bf16_f32 v44, v34, v35
	v_pk_mul_f32 v[34:35], v[36:37], v[50:51] op_sel_hi:[1,0]
	s_waitcnt lgkmcnt(0)
; __device__ __forceinline__ unsigned cvt_pk_bf16(float lo, float hi) { unsigned r; asm volatile("v_cvt_pk_bf16_f32 %0, %1, %2" : "=v"(r) : "v"(lo), "v"(hi)); return r; }
; __device__ __forceinline__ void rs_reduce(const RsLoad& L, float& r0, float& r1) {
;     const f32x4 t0 = (L.a0 + L.b0) + (L.c0 + L.d0), t1 = (L.a1 + L.b1) + (L.c1 + L.d1);
;     r0 = rsqrtf(((t0.x + t0.y) + (t0.z + t0.w)) * (1.0f / 1024.0f) + EPS); r1 = rsqrtf(((t1.x + t1.y) + (t1.z + t1.w)) * (1.0f / 1024.0f) + EPS);
; }
;     __device__ __forceinline__ void operator()(Acc& acc, const Unit& u, int wr, int wc, int fr, int fq, LAS unsigned char*, const LAS float* rst) const {
;     ...
;             for (int m = 0; m < 4; ++m) {
;                 const int row = row0 + ai * 128 + m * 16; const float rs = rsv[ai][m];
;                 const float cexp = -1.4426950408889634f * rs, rs2 = rs * rs;
;                 unsigned w[4];
; #pragma unroll
;                 for (int n = 0; n < 2; ++n)
; #pragma unroll
;                     for (int p = 0; p < 2; ++p) { const f32x2 g2 = {acc[ai][0][m][n][2 * p], acc[ai][0][m][n][2 * p + 1]}, u2 = {acc[ai][1][m][n][2 * p], acc[ai][1][m][n][2 * p + 1]};
;                         f32x2 e2 = g2 * cexp; e2.x = __builtin_amdgcn_exp2f(e2.x); e2.y = __builtin_amdgcn_exp2f(e2.y);
;                         const f32x2 d2 = e2 + 1.0f; f32x2 r2; r2.x = __builtin_amdgcn_rcpf(d2.x); r2.y = __builtin_amdgcn_rcpf(d2.y);
;                         const f32x2 o2 = ((g2 * u2) * rs2) * r2; w[n * 2 + p] = cvt_pk_bf16(o2.x, o2.y); }
;                 *(u32x4*)(O + (size_t)row * FF + col0) = (u32x4){w[0], w[1], w[2], w[3]};
	v_mul_f32_e32 v36, 0xbfb8aa3b, v126
	v_rcp_f32_e32 v40, v40
	v_rcp_f32_e32 v41, v41
	v_pk_mul_f32 v[30:31], v[30:31], v[36:37] op_sel_hi:[1,0]
	v_pk_mul_f32 v[32:33], v[32:33], v[36:37] op_sel_hi:[1,0]
	v_exp_f32_e32 v30, v30
	v_exp_f32_e32 v31, v31
	v_pk_mul_f32 v[34:35], v[34:35], v[40:41]
	v_exp_f32_e32 v32, v32
	v_cvt_pk_bf16_f32 v45, v34, v35
	v_add_u32_e32 v34, 0x90, v195
	v_pk_add_f32 v[30:31], v[30:31], 1.0 op_sel_hi:[1,0]
	v_mad_i64_i32 v[34:35], s[0:1], v34, s80, v[114:115]
	v_rcp_f32_e32 v30, v30
	v_rcp_f32_e32 v31, v31
	v_exp_f32_e32 v33, v33
	v_lshl_add_u64 v[34:35], v[34:35], 0, v[116:117]
	global_store_dwordx4 v[34:35], v[42:45], off sc1
	v_mul_f32_e32 v34, v126, v126
	v_pk_mul_f32 v[26:27], v[26:27], v[34:35] op_sel_hi:[1,0]
	v_pk_mul_f32 v[22:23], v[22:23], v[36:37] op_sel_hi:[1,0]
	v_pk_mul_f32 v[26:27], v[26:27], v[30:31]
	v_pk_add_f32 v[30:31], v[32:33], 1.0 op_sel_hi:[1,0]
	v_exp_f32_e32 v22, v22
	v_rcp_f32_e32 v30, v30
	v_rcp_f32_e32 v31, v31
	v_exp_f32_e32 v23, v23
	v_pk_mul_f32 v[28:29], v[28:29], v[34:35] op_sel_hi:[1,0]
	v_cvt_pk_bf16_f32 v26, v26, v27
	v_pk_mul_f32 v[18:19], v[18:19], v[34:35] op_sel_hi:[1,0]
	v_pk_mul_f32 v[28:29], v[28:29], v[30:31]
	v_pk_add_f32 v[22:23], v[22:23], 1.0 op_sel_hi:[1,0]
	v_cvt_pk_bf16_f32 v27, v28, v29
	v_pk_mul_f32 v[28:29], v[24:25], v[36:37] op_sel_hi:[1,0]
	v_rcp_f32_e32 v22, v22
	v_rcp_f32_e32 v23, v23
	v_exp_f32_e32 v28, v28
	v_exp_f32_e32 v29, v29
	v_pk_mul_f32 v[20:21], v[24:25], v[20:21]
	v_pk_mul_f32 v[18:19], v[18:19], v[22:23]
	v_pk_mul_f32 v[10:11], v[14:15], v[10:11]
	v_pk_add_f32 v[24:25], v[28:29], 1.0 op_sel_hi:[1,0]
	v_cvt_pk_bf16_f32 v28, v18, v19
	v_pk_mul_f32 v[18:19], v[20:21], v[34:35] op_sel_hi:[1,0]
	v_mul_f32_e32 v20, 0xbfb8aa3b, v127
	v_rcp_f32_e32 v24, v24
	v_rcp_f32_e32 v25, v25
	v_pk_mul_f32 v[22:23], v[14:15], v[20:21] op_sel_hi:[1,0]
	v_pk_mul_f32 v[14:15], v[16:17], v[20:21] op_sel_hi:[1,0]
	v_exp_f32_e32 v22, v22
	v_exp_f32_e32 v14, v14
	v_exp_f32_e32 v15, v15
	v_exp_f32_e32 v23, v23
	v_pk_mul_f32 v[18:19], v[18:19], v[24:25]
	v_pk_mul_f32 v[12:13], v[16:17], v[12:13]
	v_cvt_pk_bf16_f32 v29, v18, v19
	v_add_u32_e32 v18, 0xa0, v195
	v_pk_add_f32 v[14:15], v[14:15], 1.0 op_sel_hi:[1,0]
	v_mad_i64_i32 v[18:19], s[0:1], v18, s80, v[114:115]
	v_rcp_f32_e32 v14, v14
	v_rcp_f32_e32 v15, v15
	v_lshl_add_u64 v[18:19], v[18:19], 0, v[116:117]
	v_pk_add_f32 v[22:23], v[22:23], 1.0 op_sel_hi:[1,0]
	global_store_dwordx4 v[18:19], v[26:29], off sc1
	v_mul_f32_e32 v18, v127, v127
	v_rcp_f32_e32 v22, v22
	v_rcp_f32_e32 v23, v23
	v_pk_mul_f32 v[16:17], v[6:7], v[20:21] op_sel_hi:[1,0]
	v_pk_mul_f32 v[12:13], v[12:13], v[18:19] op_sel_hi:[1,0]
	v_exp_f32_e32 v16, v16
	v_exp_f32_e32 v17, v17
	v_pk_mul_f32 v[12:13], v[12:13], v[14:15]
	v_pk_mul_f32 v[14:15], v[8:9], v[20:21] op_sel_hi:[1,0]
	v_pk_mul_f32 v[10:11], v[10:11], v[18:19] op_sel_hi:[1,0]
	v_exp_f32_e32 v14, v14
	v_exp_f32_e32 v15, v15
	v_pk_mul_f32 v[10:11], v[10:11], v[22:23]
	v_pk_mul_f32 v[2:3], v[6:7], v[2:3]
	v_cvt_pk_bf16_f32 v10, v10, v11
	v_cvt_pk_bf16_f32 v11, v12, v13
	v_pk_add_f32 v[12:13], v[16:17], 1.0 op_sel_hi:[1,0]
	v_pk_add_f32 v[6:7], v[14:15], 1.0 op_sel_hi:[1,0]
	v_rcp_f32_e32 v12, v12
	v_rcp_f32_e32 v13, v13
	v_rcp_f32_e32 v6, v6
	v_rcp_f32_e32 v7, v7
	v_pk_mul_f32 v[2:3], v[2:3], v[18:19] op_sel_hi:[1,0]
	v_pk_mul_f32 v[4:5], v[8:9], v[4:5]
	v_pk_mul_f32 v[2:3], v[2:3], v[12:13]
	s_waitcnt vmcnt(7)
	v_pk_add_f32 v[8:9], v[148:149], v[152:153]
	v_cvt_pk_bf16_f32 v12, v2, v3
	v_pk_mul_f32 v[2:3], v[4:5], v[18:19] op_sel_hi:[1,0]
	v_pk_add_f32 v[4:5], v[156:157], v[160:161]
	v_pk_mul_f32 v[2:3], v[2:3], v[6:7]
	v_pk_add_f32 v[6:7], v[154:155], v[158:159]
	v_pk_add_f32 v[14:15], v[146:147], v[150:151]
	v_pk_add_f32 v[4:5], v[4:5], v[8:9]
	v_pk_add_f32 v[6:7], v[6:7], v[14:15]
	v_pk_add_f32 v[8:9], v[140:141], v[144:145]
	v_pk_add_f32 v[14:15], v[138:139], v[142:143]
	v_pk_add_f32 v[16:17], v[132:133], v[136:137]
	v_pk_add_f32 v[18:19], v[130:131], v[134:135]
	v_pk_add_f32 v[8:9], v[8:9], v[16:17]
	v_pk_add_f32 v[14:15], v[14:15], v[18:19]
	v_pk_mov_b32 v[16:17], v[6:7], v[4:5] op_sel:[1,0]
	v_mov_b32_e32 v7, v5
	v_pk_add_f32 v[4:5], v[16:17], v[6:7]
	v_pk_mov_b32 v[6:7], v[14:15], v[8:9] op_sel:[1,0]
	v_mov_b32_e32 v15, v9
	v_pk_add_f32 v[6:7], v[6:7], v[14:15]
	v_mov_b32_e32 v9, v4
	v_mov_b32_e32 v8, v6
	v_mov_b32_e32 v4, v7
	v_pk_add_f32 v[4:5], v[8:9], v[4:5]
	v_cvt_pk_bf16_f32 v13, v2, v3
	v_add_u32_e32 v2, 0xb0, v195
	v_pk_fma_f32 v[4:5], v[4:5], s[82:83], v[162:163] op_sel_hi:[1,0,0]
	v_mad_i64_i32 v[2:3], s[0:1], v2, s80, v[114:115]
	v_mul_f32_e32 v6, 0x4b800000, v5
	v_cmp_gt_f32_e32 vcc, s69, v5
	v_cmp_gt_f32_e64 s[0:1], s69, v4
	v_lshl_add_u64 v[2:3], v[2:3], 0, v[116:117]
	v_cndmask_b32_e32 v5, v5, v6, vcc
	v_mul_f32_e32 v6, 0x4b800000, v4
	v_cndmask_b32_e64 v4, v4, v6, s[0:1]
	v_rsq_f32_e32 v5, v5
	v_rsq_f32_e32 v4, v4
	global_store_dwordx4 v[2:3], v[10:13], off sc1
	v_mul_f32_e32 v2, 0x45800000, v5
	v_mul_f32_e32 v3, 0x45800000, v4
	v_cndmask_b32_e32 v2, v5, v2, vcc
	v_cndmask_b32_e64 v3, v4, v3, s[0:1]
	ds_write2st64_b32 v181, v2, v3 offset1:1
	s_andn2_b64 vcc, exec, s[90:91]
	s_mov_b64 s[0:1], -1
	s_cbranch_vccnz .LBB0_766
